# attention unit prologue/epilogue de-serialized: ticket atomic flies under epilogue, staging LDS reads batched, subln weight + key-norm loads hoisted
# speedup vs baseline: 1.0089x; 1.0025x over previous
.LBB0_152:
	s_or_b64 exec, exec, s[0:1]
	v_readlane_b32 s0, v254, 53
	s_waitcnt lgkmcnt(0)
	s_barrier
	v_mov_b32_e32 v0, s0
	ds_read_b32 v0, v0
	s_mov_b64 s[0:1], -1
	s_waitcnt lgkmcnt(0)
	v_readfirstlane_b32 s36, v0
	s_cmpk_gt_i32 s36, 0x77
	s_cbranch_scc1 .LBB0_149
	s_cmpk_lt_i32 s36, 0x60
	s_cbranch_scc0 .LBB0_222
	s_ashr_i32 s0, s36, 2
	s_and_b32 s0, s0, -4
	s_lshr_b32 s0, 0x405132, s0
	s_and_b32 s3, s36, 15
	s_and_b32 s5, s0, 7
	s_lshl_b32 s37, s3, 7
	v_readlane_b32 s0, v254, 37
	v_and_b32_e32 v149, 31, v148
	s_or_b32 s4, s37, s0
	s_waitcnt vmcnt(2)
	v_or_b32_e32 v48, s4, v149
	v_or_b32_e32 v1, s33, v48
	v_mov_b64_e32 v[2:3], s[72:73]
	s_movk_i32 s0, 0x1080
	v_mad_u64_u32 v[2:3], s[0:1], v1, s0, v[2:3]
	s_lshl_b32 s34, s5, 7
	v_readlane_b32 s0, v251, 13
	v_bfe_u32 v0, v148, 5, 1
	v_lshl_add_u64 v[2:3], v[2:3], 0, s[34:35]
	s_lshl_b32 s34, s0, 1
	v_lshl_add_u64 v[2:3], v[2:3], 0, s[34:35]
	v_lshlrev_b32_e32 v4, 4, v0
	v_mov_b32_e32 v5, v65
	v_lshl_add_u64 v[2:3], v[2:3], 0, v[4:5]
	v_readlane_b32 s6, v251, 31
	s_nop 3
	s_add_i32 s6, s5, s6
	s_lshl_b32 s6, s6, 3
	v_mov_b32_e32 v12, s6
	v_readlane_b32 s6, v251, 29
	v_readlane_b32 s7, v251, 30
	s_nop 4
	global_load_dwordx2 v[10:11], v12, s[6:7]
	global_load_dwordx4 v[70:73], v[2:3], off
	global_load_dwordx4 v[66:69], v[2:3], off offset:32
	v_and_b32_e32 v150, 63, v148
	s_lshl_b32 s2, s5, 6
	v_cmp_eq_u32_e32 vcc, 0, v150
	s_waitcnt vmcnt(1)
	v_and_b32_e32 v2, 0xffff0000, v70
	v_lshlrev_b32_e32 v1, 16, v70
	v_mul_f32_e32 v2, v2, v2
	v_fmac_f32_e32 v2, v1, v1
	v_lshlrev_b32_e32 v1, 16, v71
	v_fmac_f32_e32 v2, v1, v1
	v_and_b32_e32 v1, 0xffff0000, v71
	v_fmac_f32_e32 v2, v1, v1
	v_lshlrev_b32_e32 v1, 16, v72
	v_fmac_f32_e32 v2, v1, v1
	v_and_b32_e32 v1, 0xffff0000, v72
	v_fmac_f32_e32 v2, v1, v1
	v_lshlrev_b32_e32 v1, 16, v73
	v_fmac_f32_e32 v2, v1, v1
	v_and_b32_e32 v1, 0xffff0000, v73
	v_fmac_f32_e32 v2, v1, v1
	s_waitcnt vmcnt(0)
	v_lshlrev_b32_e32 v1, 16, v66
	v_fmac_f32_e32 v2, v1, v1
	v_and_b32_e32 v1, 0xffff0000, v66
	v_fmac_f32_e32 v2, v1, v1
	v_lshlrev_b32_e32 v1, 16, v67
	v_fmac_f32_e32 v2, v1, v1
	v_and_b32_e32 v1, 0xffff0000, v67
	v_fmac_f32_e32 v2, v1, v1
	v_lshlrev_b32_e32 v1, 16, v68
	v_fmac_f32_e32 v2, v1, v1
	v_and_b32_e32 v1, 0xffff0000, v68
	v_fmac_f32_e32 v2, v1, v1
	v_lshlrev_b32_e32 v1, 16, v69
	v_fmac_f32_e32 v2, v1, v1
	v_and_b32_e32 v1, 0xffff0000, v69
	v_fmac_f32_e32 v2, v1, v1
	v_mov_b32_e32 v1, v2
	s_nop 1
	v_permlane32_swap_b32_e32 v2, v1
	v_add_f32_e32 v1, v2, v1
	ds_swizzle_b32 v2, v1 offset:swizzle(SWAP,1)
	s_waitcnt lgkmcnt(0)
	v_max_f32_e32 v2, v2, v2
	v_max_f32_e32 v1, v1, v2
	ds_swizzle_b32 v2, v1 offset:swizzle(SWAP,2)
	s_waitcnt lgkmcnt(0)
	v_max_f32_e32 v2, v2, v2
	v_max_f32_e32 v1, v1, v2
	ds_swizzle_b32 v2, v1 offset:swizzle(SWAP,4)
	s_waitcnt lgkmcnt(0)
	v_max_f32_e32 v2, v2, v2
	v_max_f32_e32 v1, v1, v2
	ds_swizzle_b32 v2, v1 offset:swizzle(SWAP,8)
	s_waitcnt lgkmcnt(0)
	v_max_f32_e32 v2, v2, v2
	v_max_f32_e32 v1, v1, v2
	ds_swizzle_b32 v2, v1 offset:swizzle(SWAP,16)
	s_and_saveexec_b64 s[0:1], vcc
	s_cbranch_execz .LBB0_156
	s_waitcnt lgkmcnt(0)
	v_max_f32_e32 v2, v2, v2
	v_max_f32_e32 v1, v1, v1
	v_readlane_b32 s6, v251, 12
	v_max_f32_e32 v1, v1, v2
	s_nop 0
	v_mov_b32_e32 v2, s6
	ds_write_b32 v2, v1
.LBB0_156:
	s_or_b64 exec, exec, s[0:1]
	s_lshl_b32 s0, s5, 1
	s_cmp_lt_u32 s5, 4
	v_readlane_b32 s6, v251, 31
	s_cselect_b32 s1, -2, 7
	s_add_i32 s5, s5, s6
	s_lshl_b32 s5, s5, 3
	v_readlane_b32 s6, v251, 29
	v_mov_b32_e32 v1, s5
	v_readlane_b32 s7, v251, 30
	s_waitcnt lgkmcnt(0)
	s_barrier
	v_readlane_b32 s5, v254, 54
	v_lshrrev_b32_e32 v3, 2, v150
	s_nop 0
	v_readlane_b32 s6, v252, 9
	v_mov_b32_e32 v1, s5
	v_readlane_b32 s5, v251, 13
	v_mov_b32_e32 v2, s6
	s_movk_i32 s6, 0x1080
	v_mad_u32_u24 v153, v150, s6, v2
	v_readlane_b32 s6, v251, 18
	v_mov_b32_e32 v4, s5
	s_mul_i32 s5, s3, 0x84000
	v_or_b32_e32 v2, s6, v3
	s_lshl_b32 s58, s3, 1
	s_lshr_b32 s67, s4, 6
	s_add_i32 s3, 0, 0x20800
	s_movk_i32 s4, 0x840
	v_lshlrev_b32_e32 v5, 3, v148
	v_mad_u32_u24 v13, v2, s4, v4
	v_mov_b32_e32 v2, s3
	v_and_b32_e32 v12, 24, v5
	ds_read_b128 v[2:5], v2
	ds_read_b128 v[6:9], v1
	s_sub_i32 s0, s1, s0
	v_or_b32_e32 v1, v13, v12
	v_ldexp_f32 v13, 1.0, s0
	s_waitcnt lgkmcnt(1)
	v_max_f32_e32 v5, v5, v5
	v_max_f32_e32 v4, v4, v4
	s_waitcnt lgkmcnt(0)
	v_max_f32_e32 v9, v9, v9
	v_max_f32_e32 v8, v8, v8
	v_max_f32_e32 v4, v4, v5
	v_max_f32_e32 v5, v8, v9
	v_max3_f32 v2, v2, v3, v4
	v_max3_f32 v3, v6, v7, v5
	s_mov_b32 s0, 0xf800000
	v_mul_f32_e32 v120, 0x3fb8aa3b, v13
	v_lshlrev_b32_e32 v154, 1, v1
	v_add_u32_e32 v14, s5, v153
	v_add_u32_e32 v1, s5, v154
	v_readlane_b32 s7, v252, 10
	v_readlane_b32 s7, v251, 22
	v_cvt_f32_u32_e32 v155, v48
	v_lshlrev_b32_e32 v151, 2, v0
	s_mov_b64 s[28:29], -1
	s_waitcnt vmcnt(0)
	v_mul_f32_e32 v2, v2, v10
	v_mul_f32_e32 v3, v3, v11
	v_max_f32_e32 v2, v2, v3
	v_mul_f32_e32 v3, 0x4f800000, v2
	v_cmp_gt_f32_e32 vcc, s0, v2
	s_nop 1
	v_cndmask_b32_e32 v2, v2, v3, vcc
	v_sqrt_f32_e32 v3, v2
	s_nop 0
	v_add_u32_e32 v4, -1, v3
	v_add_u32_e32 v5, 1, v3
	v_fma_f32 v6, -v4, v3, v2
	v_fma_f32 v7, -v5, v3, v2
	v_cmp_ge_f32_e64 s[0:1], 0, v6
	s_nop 1
	v_cndmask_b32_e64 v3, v3, v4, s[0:1]
	v_cmp_lt_f32_e64 s[0:1], 0, v7
	s_nop 1
	v_cndmask_b32_e64 v3, v3, v5, s[0:1]
	v_mul_f32_e32 v4, 0x37800000, v3
	v_cndmask_b32_e32 v3, v3, v4, vcc
	v_cmp_class_f32_e32 vcc, v2, v235
	s_mov_b32 s0, 0x42400000
	s_nop 0
	v_cndmask_b32_e32 v2, v3, v2, vcc
	v_mul_f32_e32 v2, 0x3f8147ae, v2
	v_cmp_gt_f32_e32 vcc, s0, v2
	v_fmaak_f32 v4, 2.0, v2, 0x43200000
	v_readfirstlane_b32 s0, v2
	v_cndmask_b32_e64 v3, 0, 1, vcc
	v_mov_b32_e32 v2, 0x43200000
	v_readfirstlane_b32 s1, v3
	s_bitcmp1_b32 s1, 0
	s_cselect_b64 vcc, -1, 0
	v_cndmask_b32_e32 v2, v4, v2, vcc
	s_lshl_b32 s34, s2, 1
	v_div_scale_f32 v4, s[2:3], v120, v120, v2
	v_rcp_f32_e32 v6, v4
	v_cndmask_b32_e64 v3, v240, 1.0, vcc
	v_div_scale_f32 v5, vcc, v2, v120, v2
	v_fma_f32 v7, -v4, v6, 1.0
	v_fmac_f32_e32 v6, v7, v6
	v_mul_f32_e32 v7, v5, v6
	v_fma_f32 v8, -v4, v7, v5
	v_fmac_f32_e32 v7, v8, v6
	v_fma_f32 v4, -v4, v7, v5
	v_div_fmas_f32 v4, v4, v6, v7
	v_div_fixup_f32 v2, v4, v120, v2
	v_add_f32_e32 v2, v3, v2
	v_min_f32_e32 v2, 0x45800000, v2
	s_and_b32 s4, s1, 1
	v_readlane_b32 s1, v251, 14
	v_cvt_i32_f32_e32 v2, v2
	s_add_u32 s2, s1, s34
	v_readlane_b32 s1, v251, 15
	s_addc_u32 s3, s1, 0
	v_readlane_b32 s1, v251, 16
	s_add_u32 s22, s1, s34
	s_mov_b32 m0, s25
	s_nop 0
	global_load_lds_dwordx4 v14, s[2:3]
	v_readlane_b32 s1, v251, 17
	s_addc_u32 s23, s1, 0
	v_readlane_b32 s1, v251, 20
	s_mov_b32 m0, s1
	s_nop 0
	global_load_lds_dwordx4 v1, s[22:23]
	v_sub_u32_e32 v1, s37, v2
	v_add_u32_e32 v2, s37, v2
	v_add_u32_e32 v2, 0x7f, v2
	v_ashrrev_i32_e32 v1, 6, v1
	v_ashrrev_i32_e32 v2, 6, v2
	v_max_i32_e32 v1, 0, v1
	v_min_i32_e32 v2, 31, v2
	v_readfirstlane_b32 s42, v1
	v_sub_u32_e32 v1, v2, v1
	s_or_b32 s5, s58, 1
	v_readfirstlane_b32 s1, v1
	s_add_i32 s43, s1, s42
	s_cmp_eq_u32 s58, s43
	s_cselect_b32 s48, s42, s5
	s_add_i32 s5, s48, 1
	s_mul_i32 s6, s48, 0x42000
	s_cmp_eq_u32 s48, s43
	v_add_u32_e32 v1, s6, v153
	v_add_u32_e32 v2, s6, v154
	s_cselect_b32 s5, s42, s5
	v_readlane_b32 s6, v251, 21
	s_mov_b32 m0, s6
	s_nop 0
	global_load_lds_dwordx4 v1, s[2:3]
	s_add_i32 s6, s5, 1
	s_cmp_eq_u32 s5, s43
	s_mov_b32 m0, s7
	s_nop 0
	global_load_lds_dwordx4 v2, s[22:23]
	s_mul_i32 s7, s5, 0x42000
	s_cselect_b32 s5, s42, s6
	s_add_i32 s6, s5, 1
	v_add_u32_e32 v1, s7, v153
	v_add_u32_e32 v2, s7, v154
	s_mov_b32 m0, s75
	s_nop 0
	global_load_lds_dwordx4 v1, s[2:3]
	v_readlane_b32 s7, v251, 23
	s_cmp_eq_u32 s5, s43
	s_mov_b32 m0, s7
	s_nop 0
	global_load_lds_dwordx4 v2, s[22:23]
	s_mul_i32 s7, s5, 0x42000
	s_cselect_b32 s5, s42, s6
	s_add_i32 s6, s5, 1
	v_add_u32_e32 v1, s7, v153
	v_add_u32_e32 v2, s7, v154
	s_mov_b32 m0, s74
	s_nop 0
	global_load_lds_dwordx4 v1, s[2:3]
	v_readlane_b32 s7, v251, 24
	s_cmp_eq_u32 s5, s43
	s_mov_b32 m0, s7
	s_nop 0
	global_load_lds_dwordx4 v2, s[22:23]
	s_mul_i32 s7, s5, 0x42000
	s_cselect_b32 s5, s42, s6
	s_add_i32 s6, s5, 1
	v_add_u32_e32 v1, s7, v153
	v_add_u32_e32 v2, s7, v154
	s_mov_b32 m0, s92
	s_nop 0
	global_load_lds_dwordx4 v1, s[2:3]
	v_readlane_b32 s7, v251, 25
	s_cmp_eq_u32 s5, s43
	s_mov_b32 m0, s7
	s_nop 0
	global_load_lds_dwordx4 v2, s[22:23]
	s_mul_i32 s7, s5, 0x42000
	s_cselect_b32 s59, s42, s6
	s_add_i32 s5, 0, 0x10000
	v_add_u32_e32 v1, s7, v153
	s_mov_b32 m0, s78
	s_nop 0
	global_load_lds_dwordx4 v1, s[2:3]
	s_cmp_eq_u32 s4, 0
	v_readlane_b32 s4, v251, 26
	v_add_u32_e32 v1, s7, v154
	s_mov_b32 m0, s4
	s_nop 0
	global_load_lds_dwordx4 v1, s[22:23]
	v_readlane_b32 s4, v251, 27
	v_lshlrev_b32_e32 v2, 4, v149
	s_nop 0
	v_or_b32_e32 v1, s4, v0
	v_lshlrev_b32_e32 v1, 10, v1
	v_add3_u32 v156, 0, v1, v2
	v_lshlrev_b32_e32 v1, 1, v148
	v_lshrrev_b32_e32 v0, 2, v148
	v_and_b32_e32 v1, 32, v1
	v_and_or_b32 v0, v0, 3, v151
	v_add_u32_e32 v1, s5, v1
	v_lshlrev_b32_e32 v0, 6, v0
	v_add3_u32 v152, v1, v12, v0
	s_cbranch_scc0 .LBB0_196
	s_waitcnt vmcnt(10)
	s_barrier
	s_mul_i32 s4, s59, 0x42000
	v_add_u32_e32 v0, s4, v153
	s_mov_b32 m0, s80
	s_nop 0
	global_load_lds_dwordx4 v0, s[2:3]
	v_add_u32_e32 v0, s4, v154
	v_readlane_b32 s4, v251, 28
	s_mov_b32 m0, s4
	s_nop 0
	global_load_lds_dwordx4 v0, s[22:23]
	ds_read_b128 v[44:47], v156
	ds_read_b128 v[36:39], v156 offset:512
	ds_read_b128 v[32:35], v156 offset:2048
	ds_read_b128 v[40:43], v156 offset:2560
	v_or_b32_e32 v0, s37, v151
	v_sub_u32_e32 v48, v0, v48
	v_cvt_f32_i32_e32 v49, v48
	s_cmp_lg_u32 s58, s67
	s_cbranch_scc0 .LBB0_159
	s_cmp_gt_u32 s58, s67
	s_cselect_b64 s[4:5], -1, 0
	v_cndmask_b32_e64 v4, v120, -v120, s[4:5]
	s_mov_b32 s4, 2.0
	v_mul_f32_e32 v0, v4, v49
	v_fma_f32 v1, v4, v49, v4
	s_mov_b32 s5, 0x40400000
	v_pk_fma_f32 v[2:3], v[4:5], s[4:5], v[0:1] op_sel_hi:[0,1,0]
	v_mul_f32_e32 v14, 0x41000000, v4
	v_mul_f32_e32 v28, 0x42000000, v4
	v_pk_add_f32 v[4:5], v[14:15], v[0:1] op_sel_hi:[0,1]
	v_pk_add_f32 v[6:7], v[14:15], v[2:3] op_sel_hi:[0,1]
	v_pk_add_f32 v[8:9], v[14:15], v[4:5] op_sel_hi:[0,1]
	v_pk_add_f32 v[10:11], v[14:15], v[6:7] op_sel_hi:[0,1]
	v_pk_add_f32 v[12:13], v[14:15], v[8:9] op_sel_hi:[0,1]
	v_pk_add_f32 v[14:15], v[14:15], v[10:11] op_sel_hi:[0,1]
	v_pk_add_f32 v[18:19], v[28:29], v[2:3] op_sel_hi:[0,1]
	v_pk_add_f32 v[22:23], v[28:29], v[6:7] op_sel_hi:[0,1]
	v_pk_add_f32 v[26:27], v[28:29], v[10:11] op_sel_hi:[0,1]
	v_pk_add_f32 v[30:31], v[28:29], v[14:15] op_sel_hi:[0,1]
	v_pk_add_f32 v[16:17], v[28:29], v[0:1] op_sel_hi:[0,1]
	v_pk_add_f32 v[20:21], v[28:29], v[4:5] op_sel_hi:[0,1]
	v_pk_add_f32 v[24:25], v[28:29], v[8:9] op_sel_hi:[0,1]
	v_pk_add_f32 v[28:29], v[28:29], v[12:13] op_sel_hi:[0,1]
	s_mov_b64 s[28:29], 0

.LBB0_218:
	s_or_b64 exec, exec, s[2:3]
	v_mov_b32_e32 v32, v121

.LBB0_221:
	s_or_b64 exec, exec, s[0:1]
	s_waitcnt lgkmcnt(0)
	v_lshl_add_u32 v34, v151, 2, s79
	ds_read_b128 v[38:41], v34
	ds_read_b128 v[42:45], v34 offset:32
	ds_read_b128 v[46:49], v34 offset:64
	ds_read_b128 v[50:53], v34 offset:96
	v_lshlrev_b32_e32 v90, 4, v148
	v_and_b32_e32 v90, 48, v90
	v_lshlrev_b32_e32 v90, 2, v90
	global_load_dwordx4 v[74:77], v90, s[52:53]
	global_load_dwordx4 v[78:81], v90, s[52:53] offset:32
	global_load_dwordx4 v[82:85], v90, s[52:53] offset:16
	global_load_dwordx4 v[86:89], v90, s[52:53] offset:48
	v_lshlrev_b32_e32 v37, 2, v149
	v_readlane_b32 s0, v251, 19
	s_waitcnt lgkmcnt(0)
	v_readlane_b32 s1, v254, 37
	v_mul_f32_e32 v54, v16, v38
	v_mul_f32_e32 v55, v0, v38
	v_or_b32_e32 v56, s1, v151
	v_mul_u32_u24_e32 v56, 0x110, v56
	v_add3_u32 v56, s0, v56, v37
	ds_write2_b32 v56, v54, v55 offset1:32
	v_readlane_b32 s1, v254, 23
	v_mul_f32_e32 v57, v17, v39
	v_mul_f32_e32 v58, v1, v39
	v_or_b32_e32 v59, s1, v151
	v_mul_u32_u24_e32 v59, 0x110, v59
	v_add3_u32 v59, s0, v59, v37
	ds_write2_b32 v59, v57, v58 offset1:32
	v_readlane_b32 s1, v254, 24
	v_mul_f32_e32 v54, v18, v40
	v_mul_f32_e32 v55, v2, v40
	v_or_b32_e32 v56, s1, v151
	v_mul_u32_u24_e32 v56, 0x110, v56
	v_add3_u32 v56, s0, v56, v37
	ds_write2_b32 v56, v54, v55 offset1:32
	v_readlane_b32 s1, v254, 25
	v_mul_f32_e32 v57, v19, v41
	v_mul_f32_e32 v58, v3, v41
	v_or_b32_e32 v59, s1, v151
	v_mul_u32_u24_e32 v59, 0x110, v59
	v_add3_u32 v59, s0, v59, v37
	ds_write2_b32 v59, v57, v58 offset1:32
	v_readlane_b32 s1, v254, 26
	v_mul_f32_e32 v54, v20, v42
	v_mul_f32_e32 v55, v4, v42
	v_or_b32_e32 v56, s1, v151
	v_mul_u32_u24_e32 v56, 0x110, v56
	v_add3_u32 v56, s0, v56, v37
	ds_write2_b32 v56, v54, v55 offset1:32
	v_readlane_b32 s1, v254, 27
	v_mul_f32_e32 v57, v21, v43
	v_mul_f32_e32 v58, v5, v43
	v_or_b32_e32 v59, s1, v151
	v_mul_u32_u24_e32 v59, 0x110, v59
	v_add3_u32 v59, s0, v59, v37
	ds_write2_b32 v59, v57, v58 offset1:32
	v_readlane_b32 s1, v254, 28
	v_mul_f32_e32 v54, v22, v44
	v_mul_f32_e32 v55, v6, v44
	v_or_b32_e32 v56, s1, v151
	v_mul_u32_u24_e32 v56, 0x110, v56
	v_add3_u32 v56, s0, v56, v37
	ds_write2_b32 v56, v54, v55 offset1:32
	v_readlane_b32 s1, v254, 29
	v_mul_f32_e32 v57, v23, v45
	v_mul_f32_e32 v58, v7, v45
	v_or_b32_e32 v59, s1, v151
	v_mul_u32_u24_e32 v59, 0x110, v59
	v_add3_u32 v59, s0, v59, v37
	ds_write2_b32 v59, v57, v58 offset1:32
	v_readlane_b32 s1, v254, 30
	v_mul_f32_e32 v54, v24, v46
	v_mul_f32_e32 v55, v8, v46
	v_or_b32_e32 v56, s1, v151
	v_mul_u32_u24_e32 v56, 0x110, v56
	v_add3_u32 v56, s0, v56, v37
	ds_write2_b32 v56, v54, v55 offset1:32
	v_readlane_b32 s1, v254, 31
	v_mul_f32_e32 v57, v25, v47
	v_mul_f32_e32 v58, v9, v47
	v_or_b32_e32 v59, s1, v151
	v_mul_u32_u24_e32 v59, 0x110, v59
	v_add3_u32 v59, s0, v59, v37
	ds_write2_b32 v59, v57, v58 offset1:32
	v_readlane_b32 s1, v254, 32
	v_mul_f32_e32 v54, v26, v48
	v_mul_f32_e32 v55, v10, v48
	v_or_b32_e32 v56, s1, v151
	v_mul_u32_u24_e32 v56, 0x110, v56
	v_add3_u32 v56, s0, v56, v37
	ds_write2_b32 v56, v54, v55 offset1:32
	v_readlane_b32 s1, v254, 33
	v_mul_f32_e32 v57, v27, v49
	v_mul_f32_e32 v58, v11, v49
	v_or_b32_e32 v59, s1, v151
	v_mul_u32_u24_e32 v59, 0x110, v59
	v_add3_u32 v59, s0, v59, v37
	ds_write2_b32 v59, v57, v58 offset1:32
	v_readlane_b32 s1, v254, 34
	v_mul_f32_e32 v54, v28, v50
	v_mul_f32_e32 v55, v12, v50
	v_or_b32_e32 v56, s1, v151
	v_mul_u32_u24_e32 v56, 0x110, v56
	v_add3_u32 v56, s0, v56, v37
	ds_write2_b32 v56, v54, v55 offset1:32
	v_readlane_b32 s1, v254, 35
	v_mul_f32_e32 v57, v29, v51
	v_mul_f32_e32 v58, v13, v51
	v_or_b32_e32 v59, s1, v151
	v_mul_u32_u24_e32 v59, 0x110, v59
	v_add3_u32 v59, s0, v59, v37
	ds_write2_b32 v59, v57, v58 offset1:32
	v_readlane_b32 s1, v254, 36
	v_mul_f32_e32 v54, v30, v52
	v_mul_f32_e32 v55, v14, v52
	v_or_b32_e32 v56, s1, v151
	v_mul_u32_u24_e32 v56, 0x110, v56
	v_add3_u32 v56, s0, v56, v37
	ds_write2_b32 v56, v54, v55 offset1:32
	v_readlane_b32 s1, v254, 38
	v_mul_f32_e32 v57, v31, v53
	v_mul_f32_e32 v58, v15, v53
	v_or_b32_e32 v59, s1, v151
	v_mul_u32_u24_e32 v59, 0x110, v59
	v_add3_u32 v59, s0, v59, v37
	ds_write2_b32 v59, v57, v58 offset1:32
	v_ashrrev_i32_e32 v50, 2, v148
	v_lshlrev_b32_e32 v0, 4, v148
	v_and_b32_e32 v52, 48, v0
	v_lshlrev_b32_e32 v16, 2, v52
	s_waitcnt lgkmcnt(0)
	s_barrier
	s_movk_i32 s0, 0x110
	v_mul_lo_u32 v17, v50, s0
	v_add3_u32 v46, 0, v17, v16
	ds_read_b128 v[16:19], v46 offset:32
	ds_read_b128 v[20:23], v46 offset:48
	ds_read_b128 v[24:27], v46 offset:34864
	ds_read_b128 v[28:31], v46
	ds_read_b128 v[34:37], v46 offset:16
	ds_read_b128 v[38:41], v46 offset:34832
	ds_read_b128 v[42:45], v46 offset:34848
	ds_read_b128 v[46:49], v46 offset:34816
	s_waitcnt lgkmcnt(5)
	v_pk_fma_f32 v[20:21], v[110:111], v[24:25], v[20:21] neg_lo:[1,0,0] neg_hi:[1,0,0]
	v_pk_fma_f32 v[22:23], v[110:111], v[26:27], v[22:23] neg_lo:[1,0,0] neg_hi:[1,0,0]
	s_waitcnt lgkmcnt(2)
	v_pk_fma_f32 v[34:35], v[110:111], v[38:39], v[34:35] neg_lo:[1,0,0] neg_hi:[1,0,0]
	v_pk_fma_f32 v[36:37], v[110:111], v[40:41], v[36:37] neg_lo:[1,0,0] neg_hi:[1,0,0]
	s_waitcnt lgkmcnt(0)
	v_pk_fma_f32 v[28:29], v[110:111], v[46:47], v[28:29] neg_lo:[1,0,0] neg_hi:[1,0,0]
	v_pk_fma_f32 v[30:31], v[110:111], v[48:49], v[30:31] neg_lo:[1,0,0] neg_hi:[1,0,0]
	v_pk_mul_f32 v[46:47], v[28:29], v[28:29]
	v_pk_mul_f32 v[48:49], v[30:31], v[30:31]
	v_add_f32_e32 v46, v46, v47
	v_add_f32_e32 v46, v46, v48
	v_pk_mul_f32 v[38:39], v[34:35], v[34:35]
	v_add_f32_e32 v46, v46, v49
	v_add_f32_e32 v38, v46, v38
	v_pk_mul_f32 v[40:41], v[36:37], v[36:37]
	v_add_f32_e32 v38, v38, v39
	v_pk_fma_f32 v[16:17], v[110:111], v[42:43], v[16:17] neg_lo:[1,0,0] neg_hi:[1,0,0]
	v_add_f32_e32 v38, v38, v40
	v_pk_mul_f32 v[42:43], v[16:17], v[16:17]
	v_add_f32_e32 v38, v38, v41
	v_pk_fma_f32 v[18:19], v[110:111], v[44:45], v[18:19] neg_lo:[1,0,0] neg_hi:[1,0,0]
	v_add_f32_e32 v38, v38, v42
	v_pk_mul_f32 v[44:45], v[18:19], v[18:19]
	v_add_f32_e32 v38, v38, v43
	v_add_f32_e32 v38, v38, v44
	v_pk_mul_f32 v[24:25], v[20:21], v[20:21]
	v_add_f32_e32 v38, v38, v45
	v_add_f32_e32 v24, v38, v24
	v_pk_mul_f32 v[26:27], v[22:23], v[22:23]
	v_add_f32_e32 v24, v24, v25
	v_add_f32_e32 v24, v24, v26
	v_add_f32_e32 v24, v24, v27
	ds_swizzle_b32 v25, v24 offset:swizzle(SWAP,1)
	s_mov_b32 s0, 0x800000
	v_ashrrev_i32_e32 v51, 31, v50
	s_waitcnt lgkmcnt(0)
	v_add_f32_e32 v24, v24, v25
	ds_swizzle_b32 v25, v24 offset:swizzle(SWAP,2)
	s_waitcnt lgkmcnt(0)
	v_add_f32_e32 v24, v24, v25
	v_mov_b32_e32 v25, 0x3727c5ac
	v_fmamk_f32 v24, v24, 0x3c800000, v25
	v_mul_f32_e32 v25, 0x4b800000, v24
	v_cmp_gt_f32_e32 vcc, s0, v24
	s_add_u32 s0, s37, s33
	s_addc_u32 s1, 0, 0
	v_cndmask_b32_e32 v24, v24, v25, vcc
	v_rsq_f32_e32 v24, v24
	s_nop 0
	v_mul_f32_e32 v25, 0x45800000, v24
	v_cndmask_b32_e32 v24, v24, v25, vcc
	v_mul_f32_e32 v24, v147, v24
	v_pk_mul_f32 v[16:17], v[16:17], v[24:25] op_sel_hi:[1,0]
	v_pk_mul_f32 v[18:19], v[18:19], v[24:25] op_sel_hi:[1,0]
	v_pk_mul_f32 v[26:27], v[28:29], v[24:25] op_sel_hi:[1,0]
	v_pk_mul_f32 v[28:29], v[30:31], v[24:25] op_sel_hi:[1,0]
	v_pk_mul_f32 v[30:31], v[34:35], v[24:25] op_sel_hi:[1,0]
	v_pk_mul_f32 v[34:35], v[36:37], v[24:25] op_sel_hi:[1,0]
	v_pk_mul_f32 v[20:21], v[20:21], v[24:25] op_sel_hi:[1,0]
	s_waitcnt vmcnt(3)
	v_pk_mul_f32 v[0:1], v[74:75], v[26:27]
	s_waitcnt vmcnt(2)
	v_pk_mul_f32 v[4:5], v[78:79], v[16:17]
	v_pk_mul_f32 v[16:17], v[22:23], v[24:25] op_sel_hi:[1,0]
	v_pk_mul_f32 v[6:7], v[80:81], v[18:19]
	s_waitcnt vmcnt(0)
	v_pk_mul_f32 v[14:15], v[16:17], v[88:89]
	v_lshl_add_u64 v[16:17], s[0:1], 0, v[50:51]
	v_readlane_b32 s0, v250, 15
	v_lshlrev_b64 v[16:17], 11, v[16:17]
	v_readlane_b32 s12, v250, 27
	v_readlane_b32 s13, v250, 28
	v_readlane_b32 s1, v250, 16
	v_lshlrev_b32_e32 v18, 1, v52
	v_lshl_add_u64 v[16:17], s[12:13], 0, v[16:17]
	v_lshl_add_u64 v[16:17], v[16:17], 0, s[34:35]
	v_mov_b32_e32 v19, v65
	v_lshl_add_u64 v[16:17], v[16:17], 0, v[18:19]
	s_mov_b64 s[0:1], 0x2000200
	v_pk_mul_f32 v[2:3], v[76:77], v[28:29]
	v_pk_mul_f32 v[8:9], v[82:83], v[30:31]
	v_lshl_add_u64 v[18:19], v[16:17], 0, s[0:1]
	s_brev_b32 s0, 64
	v_pk_mul_f32 v[10:11], v[34:35], v[84:85]
	v_cvt_pk_bf16_f32 v0, v0, v1
	v_cvt_pk_bf16_f32 v1, v2, v3
	v_cvt_pk_bf16_f32 v2, v8, v9
	v_add_co_u32_e32 v8, vcc, s0, v16
	v_pk_mul_f32 v[12:13], v[86:87], v[20:21]
	v_cvt_pk_bf16_f32 v3, v10, v11
	v_addc_co_u32_e32 v9, vcc, 0, v17, vcc
	global_store_dwordx4 v[8:9], v[0:3], off offset:512
	s_mov_b64 s[0:1], 0
	v_readlane_b32 s2, v250, 17
	v_cvt_pk_bf16_f32 v0, v4, v5
	v_cvt_pk_bf16_f32 v1, v6, v7
	v_cvt_pk_bf16_f32 v2, v12, v13
	v_cvt_pk_bf16_f32 v3, v14, v15
	v_readlane_b32 s3, v250, 18
	v_readlane_b32 s4, v250, 19
	v_readlane_b32 s5, v250, 20
	v_readlane_b32 s6, v250, 21
	v_readlane_b32 s7, v250, 22
	v_readlane_b32 s8, v250, 23
	v_readlane_b32 s9, v250, 24
	v_readlane_b32 s10, v250, 25
	v_readlane_b32 s11, v250, 26
	v_readlane_b32 s14, v250, 29
	v_readlane_b32 s15, v250, 30
	global_store_dwordx4 v[18:19], v[0:3], off offset:16
	s_barrier
